# triple-buffered tail conversion + dequeue-ahead in A-units
# baseline (speedup 1.0000x reference)
.Ltail_nm_p0:
	v_mul_lo_u32 v210, s78, v203
	v_lshl_add_u32 v209, v209, 2, v210
	v_lshl_add_u32 v210, s55, 5, v203
	v_lshlrev_b32_e32 v210, 12, v210
	s_lshl_b32 s4, s54, 7
	v_lshl_add_u32 v210, v204, 4, v210
	v_add_u32_e32 v214, s4, v210
	s_lshl_b32 s4, s54, 8
	s_add_u32 s4, s68, s4
	s_addc_u32 s5, s69, 0
	global_load_dword v96, v207, s[4:5]
	global_load_dword v97, v207, s[4:5] offset:32
	global_load_dword v98, v207, s[4:5] offset:64
	global_load_dword v99, v207, s[4:5] offset:96
	global_load_dword v100, v207, s[4:5] offset:128
	global_load_dword v101, v207, s[4:5] offset:160
	global_load_dword v102, v207, s[4:5] offset:192
	global_load_dword v103, v207, s[4:5] offset:224
	global_load_dwordx4 v[6:9], v209, s[76:77]
	s_add_u32 s76, s76, s79
	s_addc_u32 s77, s77, 0
	global_load_dwordx4 v[10:13], v209, s[76:77]
	s_add_u32 s76, s76, s79
	s_addc_u32 s77, s77, 0
	global_load_dwordx4 v[14:17], v209, s[76:77]
	s_add_u32 s76, s76, s79
	s_addc_u32 s77, s77, 0
	global_load_dwordx4 v[18:21], v209, s[76:77]
	s_add_u32 s76, s76, s79
	s_addc_u32 s77, s77, 0
	global_load_dwordx4 v[22:25], v209, s[76:77]
	s_add_u32 s76, s76, s79
	s_addc_u32 s77, s77, 0
	global_load_dwordx4 v[26:29], v209, s[76:77]
	s_add_u32 s76, s76, s79
	s_addc_u32 s77, s77, 0
	global_load_dwordx4 v[30:33], v209, s[76:77]
	s_add_u32 s76, s76, s79
	s_addc_u32 s77, s77, 0
	global_load_dwordx4 v[34:37], v209, s[76:77]
	s_mov_b32 s52, 0
	s_add_u32 s70, s70, s71
	s_cmp_lt_u32 s70, 0x2520
	s_cbranch_scc0 .Ltail_ni_p1
	s_cmp_lt_u32 s70, 0x1d20
	s_cbranch_scc0 .Ltail_m0_p1
	s_mul_hi_u32 s54, s70, 0x1194539
	s_mul_i32 s4, s54, 0xe9
	s_sub_u32 s55, s70, s4
	s_mov_b32 s47, 1
	s_movk_i32 s78, 0x7460
	s_mov_b64 s[56:57], s[64:65]
	s_mov_b64 s[50:51], s[66:67]
	s_branch .Ltail_cm_p1

.Ltail_nm_p1:
	v_mul_lo_u32 v210, s78, v203
	v_lshl_add_u32 v209, v209, 2, v210
	v_lshl_add_u32 v210, s55, 5, v203
	v_lshlrev_b32_e32 v210, 12, v210
	s_lshl_b32 s4, s54, 7
	v_lshl_add_u32 v210, v204, 4, v210
	v_add_u32_e32 v216, s4, v210
	s_lshl_b32 s4, s54, 8
	s_add_u32 s4, s68, s4
	s_addc_u32 s5, s69, 0
	global_load_dword v104, v207, s[4:5]
	global_load_dword v105, v207, s[4:5] offset:32
	global_load_dword v106, v207, s[4:5] offset:64
	global_load_dword v107, v207, s[4:5] offset:96
	global_load_dword v108, v207, s[4:5] offset:128
	global_load_dword v109, v207, s[4:5] offset:160
	global_load_dword v110, v207, s[4:5] offset:192
	global_load_dword v111, v207, s[4:5] offset:224
	global_load_dwordx4 v[38:41], v209, s[76:77]
	s_add_u32 s76, s76, s79
	s_addc_u32 s77, s77, 0
	global_load_dwordx4 v[42:45], v209, s[76:77]
	s_add_u32 s76, s76, s79
	s_addc_u32 s77, s77, 0
	global_load_dwordx4 v[46:49], v209, s[76:77]
	s_add_u32 s76, s76, s79
	s_addc_u32 s77, s77, 0
	global_load_dwordx4 v[58:61], v209, s[76:77]
	s_add_u32 s76, s76, s79
	s_addc_u32 s77, s77, 0
	global_load_dwordx4 v[62:65], v209, s[76:77]
	s_add_u32 s76, s76, s79
	s_addc_u32 s77, s77, 0
	global_load_dwordx4 v[66:69], v209, s[76:77]
	s_add_u32 s76, s76, s79
	s_addc_u32 s77, s77, 0
	global_load_dwordx4 v[88:91], v209, s[76:77]
	s_add_u32 s76, s76, s79
	s_addc_u32 s77, s77, 0
	global_load_dwordx4 v[92:95], v209, s[76:77]
	s_add_u32 s52, s52, 1
.Ltail_ni_p1:
.Ltail_loop:
	s_add_u32 s70, s70, s71
	s_cmp_lt_u32 s70, 0x2520
	s_cbranch_scc0 .Ltail_ni_r0
	s_cmp_lt_u32 s70, 0x1d20
	s_cbranch_scc0 .Ltail_m0_r0
	s_mul_hi_u32 s54, s70, 0x1194539
	s_mul_i32 s4, s54, 0xe9
	s_sub_u32 s55, s70, s4
	s_mov_b32 s58, 1
	s_movk_i32 s78, 0x7460
	s_mov_b64 s[56:57], s[64:65]
	s_mov_b64 s[60:61], s[66:67]
	s_branch .Ltail_cm_r0
.Ltail_m0_r0:
	s_sub_u32 s4, s70, 0x1d20
	s_lshr_b32 s54, s4, 6
	s_and_b32 s55, s4, 63
	s_mov_b32 s58, 0
	s_movk_i32 s78, 0x2000
	s_mov_b64 s[56:57], s[72:73]
	s_mov_b64 s[60:61], s[74:75]
.Ltail_cm_r0:
	s_lshl_b32 s4, s54, 6
	s_mul_i32 s4, s4, s78
	s_add_u32 s76, s56, s4
	s_addc_u32 s77, s57, 0
	s_lshl_b32 s79, s78, 3
	v_lshlrev_b32_e32 v210, 2, v204
	v_lshl_add_u32 v208, s55, 5, v210
	v_mov_b32_e32 v209, v208
	v_mov_b32_e32 v248, 1.0
	s_cmp_eq_u32 s58, 0
	s_cbranch_scc1 .Ltail_nm_r0
	s_movk_i32 s4, 0x13ff
	v_cmp_lt_u32_e32 vcc, s4, v208
	v_add_u32_e32 v210, 8, v208
	v_add_u32_e32 v211, 0xfffff700, v208
	v_cndmask_b32_e32 v209, v209, v210, vcc
	s_movk_i32 s4, 0x1cff
	v_cmp_lt_u32_e32 vcc, s4, v208
	v_add_u32_e32 v210, 0xffffec00, v208
	v_mov_b32_e32 v212, 0x3dd105ec
	v_cndmask_b32_e32 v209, v209, v211, vcc
	s_movk_i32 s4, 0x1d07
	v_cmp_lt_u32_e32 vcc, s4, v208
	s_movk_i32 s5, 0x180
	s_nop 0
	v_cndmask_b32_e32 v209, v209, v208, vcc
	v_cmp_gt_u32_e32 vcc, s5, v210
	s_movk_i32 s4, 0x1d17
	s_nop 0
	v_cndmask_b32_e32 v248, 1.0, v212, vcc
	v_cmp_lt_u32_e32 vcc, s4, v208
	s_nop 1
	v_cndmask_b32_e64 v209, v209, 0, vcc
	v_cndmask_b32_e64 v248, v248, 0, vcc
.Ltail_nm_r0:
	v_mul_lo_u32 v210, s78, v203
	v_lshl_add_u32 v209, v209, 2, v210
	v_lshl_add_u32 v210, s55, 5, v203
	v_lshlrev_b32_e32 v210, 12, v210
	s_lshl_b32 s4, s54, 7
	v_lshl_add_u32 v210, v204, 4, v210
	v_add_u32_e32 v249, s4, v210
	s_lshl_b32 s4, s54, 8
	s_add_u32 s4, s68, s4
	s_addc_u32 s5, s69, 0
	global_load_dword v240, v207, s[4:5]
	global_load_dword v241, v207, s[4:5] offset:32
	global_load_dword v242, v207, s[4:5] offset:64
	global_load_dword v243, v207, s[4:5] offset:96
	global_load_dword v244, v207, s[4:5] offset:128
	global_load_dword v245, v207, s[4:5] offset:160
	global_load_dword v246, v207, s[4:5] offset:192
	global_load_dword v247, v207, s[4:5] offset:224
	global_load_dwordx4 v[178:181], v209, s[76:77]
	s_add_u32 s76, s76, s79
	s_addc_u32 s77, s77, 0
	global_load_dwordx4 v[182:185], v209, s[76:77]
	s_add_u32 s76, s76, s79
	s_addc_u32 s77, s77, 0
	global_load_dwordx4 v[186:189], v209, s[76:77]
	s_add_u32 s76, s76, s79
	s_addc_u32 s77, s77, 0
	global_load_dwordx4 v[220:223], v209, s[76:77]
	s_add_u32 s76, s76, s79
	s_addc_u32 s77, s77, 0
	global_load_dwordx4 v[224:227], v209, s[76:77]
	s_add_u32 s76, s76, s79
	s_addc_u32 s77, s77, 0
	global_load_dwordx4 v[228:231], v209, s[76:77]
	s_add_u32 s76, s76, s79
	s_addc_u32 s77, s77, 0
	global_load_dwordx4 v[232:235], v209, s[76:77]
	s_add_u32 s76, s76, s79
	s_addc_u32 s77, s77, 0
	global_load_dwordx4 v[236:239], v209, s[76:77]
	s_add_u32 s52, s52, 1
.Ltail_ni_r0:
	s_cmp_eq_u32 s52, 2
	s_cbranch_scc1 .Ltail_w32_r0
	s_cmp_eq_u32 s52, 1
	s_cbranch_scc1 .Ltail_w16_r0
	s_waitcnt vmcnt(0)
	s_branch .Ltail_wd_r0
.Ltail_w32_r0:
	s_waitcnt vmcnt(32)
	s_branch .Ltail_wd_r0

.Ltail_gk_A:
	v_mul_f32_e32 v217, v96, v213
	v_mul_f32_e32 v6, v6, v217
	v_mul_f32_e32 v7, v7, v217
	v_mul_f32_e32 v8, v8, v217
	v_mul_f32_e32 v9, v9, v217
	ds_write_b32 v205, v6 offset:0
	ds_write_b32 v205, v7 offset:4
	ds_write_b32 v205, v8 offset:8
	ds_write_b32 v205, v9 offset:12
	v_mul_f32_e32 v217, v97, v213
	v_mul_f32_e32 v10, v10, v217
	v_mul_f32_e32 v11, v11, v217
	v_mul_f32_e32 v12, v12, v217
	v_mul_f32_e32 v13, v13, v217
	ds_write_b32 v205, v10 offset:1056
	ds_write_b32 v205, v11 offset:1060
	ds_write_b32 v205, v12 offset:1064
	ds_write_b32 v205, v13 offset:1068
	v_mul_f32_e32 v217, v98, v213
	v_mul_f32_e32 v14, v14, v217
	v_mul_f32_e32 v15, v15, v217
	v_mul_f32_e32 v16, v16, v217
	v_mul_f32_e32 v17, v17, v217
	ds_write_b32 v205, v14 offset:2112
	ds_write_b32 v205, v15 offset:2116
	ds_write_b32 v205, v16 offset:2120
	ds_write_b32 v205, v17 offset:2124
	v_mul_f32_e32 v217, v99, v213
	v_mul_f32_e32 v18, v18, v217
	v_mul_f32_e32 v19, v19, v217
	v_mul_f32_e32 v20, v20, v217
	v_mul_f32_e32 v21, v21, v217
	ds_write_b32 v205, v18 offset:3168
	ds_write_b32 v205, v19 offset:3172
	ds_write_b32 v205, v20 offset:3176
	ds_write_b32 v205, v21 offset:3180
	v_mul_f32_e32 v217, v100, v213
	v_mul_f32_e32 v22, v22, v217
	v_mul_f32_e32 v23, v23, v217
	v_mul_f32_e32 v24, v24, v217
	v_mul_f32_e32 v25, v25, v217
	ds_write_b32 v205, v22 offset:4224
	ds_write_b32 v205, v23 offset:4228
	ds_write_b32 v205, v24 offset:4232
	ds_write_b32 v205, v25 offset:4236
	v_mul_f32_e32 v217, v101, v213
	v_mul_f32_e32 v26, v26, v217
	v_mul_f32_e32 v27, v27, v217
	v_mul_f32_e32 v28, v28, v217
	v_mul_f32_e32 v29, v29, v217
	ds_write_b32 v205, v26 offset:5280
	ds_write_b32 v205, v27 offset:5284
	ds_write_b32 v205, v28 offset:5288
	ds_write_b32 v205, v29 offset:5292
	v_mul_f32_e32 v217, v102, v213
	v_mul_f32_e32 v30, v30, v217
	v_mul_f32_e32 v31, v31, v217
	v_mul_f32_e32 v32, v32, v217
	v_mul_f32_e32 v33, v33, v217
	ds_write_b32 v205, v30 offset:6336
	ds_write_b32 v205, v31 offset:6340
	ds_write_b32 v205, v32 offset:6344
	ds_write_b32 v205, v33 offset:6348
	v_mul_f32_e32 v217, v103, v213
	v_mul_f32_e32 v34, v34, v217
	v_mul_f32_e32 v35, v35, v217
	v_mul_f32_e32 v36, v36, v217
	v_mul_f32_e32 v37, v37, v217
	ds_write_b32 v205, v34 offset:7392
	ds_write_b32 v205, v35 offset:7396
	ds_write_b32 v205, v36 offset:7400
	ds_write_b32 v205, v37 offset:7404
	s_waitcnt lgkmcnt(0)
	ds_read2_b32 v[144:145], v206 offset0:0 offset1:33
	ds_read2_b32 v[146:147], v206 offset0:66 offset1:99
	ds_read2_b32 v[148:149], v206 offset0:132 offset1:165
	ds_read2_b32 v[150:151], v206 offset0:198 offset1:231
	s_waitcnt lgkmcnt(3)
	v_cvt_pk_bf16_f32 v152, v144, v145
	s_waitcnt lgkmcnt(2)
	v_cvt_pk_bf16_f32 v153, v146, v147
	s_waitcnt lgkmcnt(1)
	v_cvt_pk_bf16_f32 v154, v148, v149
	s_waitcnt lgkmcnt(0)
	v_cvt_pk_bf16_f32 v155, v150, v151
	s_mov_b64 s[6:7], s[48:49]
	global_store_dwordx4 v214, v[152:155], s[6:7]
	ds_read2_b32 v[144:145], v206 offset0:8 offset1:41
	ds_read2_b32 v[146:147], v206 offset0:74 offset1:107
	ds_read2_b32 v[148:149], v206 offset0:140 offset1:173
	ds_read2_b32 v[150:151], v206 offset0:206 offset1:239
	s_waitcnt lgkmcnt(3)
	v_cvt_pk_bf16_f32 v156, v144, v145
	s_waitcnt lgkmcnt(2)
	v_cvt_pk_bf16_f32 v157, v146, v147
	s_waitcnt lgkmcnt(1)
	v_cvt_pk_bf16_f32 v158, v148, v149
	s_waitcnt lgkmcnt(0)
	v_cvt_pk_bf16_f32 v159, v150, v151
	s_add_u32 s6, s6, 0x8000
	s_addc_u32 s7, s7, 0
	global_store_dwordx4 v214, v[156:159], s[6:7]
	ds_read2_b32 v[144:145], v206 offset0:16 offset1:49
	ds_read2_b32 v[146:147], v206 offset0:82 offset1:115
	ds_read2_b32 v[148:149], v206 offset0:148 offset1:181
	ds_read2_b32 v[150:151], v206 offset0:214 offset1:247
	s_waitcnt lgkmcnt(3)
	v_cvt_pk_bf16_f32 v152, v144, v145
	s_waitcnt lgkmcnt(2)
	v_cvt_pk_bf16_f32 v153, v146, v147
	s_waitcnt lgkmcnt(1)
	v_cvt_pk_bf16_f32 v154, v148, v149
	s_waitcnt lgkmcnt(0)
	v_cvt_pk_bf16_f32 v155, v150, v151
	s_add_u32 s6, s6, 0x8000
	s_addc_u32 s7, s7, 0
	global_store_dwordx4 v214, v[152:155], s[6:7]
	ds_read2_b32 v[144:145], v206 offset0:24 offset1:57
	ds_read2_b32 v[146:147], v206 offset0:90 offset1:123
	ds_read2_b32 v[148:149], v206 offset0:156 offset1:189
	ds_read2_b32 v[150:151], v206 offset0:222 offset1:255
	s_waitcnt lgkmcnt(3)
	v_cvt_pk_bf16_f32 v156, v144, v145
	s_waitcnt lgkmcnt(2)
	v_cvt_pk_bf16_f32 v157, v146, v147
	s_waitcnt lgkmcnt(1)
	v_cvt_pk_bf16_f32 v158, v148, v149
	s_waitcnt lgkmcnt(0)
	v_cvt_pk_bf16_f32 v159, v150, v151
	s_add_u32 s6, s6, 0x8000
	s_addc_u32 s7, s7, 0
	global_store_dwordx4 v214, v[156:159], s[6:7]
	s_cmp_eq_u32 s52, 0
	s_cbranch_scc1 .Ltail_end
	s_sub_u32 s52, s52, 1
	s_add_u32 s70, s70, s71
	s_cmp_lt_u32 s70, 0x2520
	s_cbranch_scc0 .Ltail_ni_r1
	s_cmp_lt_u32 s70, 0x1d20
	s_cbranch_scc0 .Ltail_m0_r1
	s_mul_hi_u32 s54, s70, 0x1194539
	s_mul_i32 s4, s54, 0xe9
	s_sub_u32 s55, s70, s4
	s_mov_b32 s46, 1
	s_movk_i32 s78, 0x7460
	s_mov_b64 s[56:57], s[64:65]
	s_mov_b64 s[48:49], s[66:67]
	s_branch .Ltail_cm_r1

.Ltail_nm_r1:
	v_mul_lo_u32 v210, s78, v203
	v_lshl_add_u32 v209, v209, 2, v210
	v_lshl_add_u32 v210, s55, 5, v203
	v_lshlrev_b32_e32 v210, 12, v210
	s_lshl_b32 s4, s54, 7
	v_lshl_add_u32 v210, v204, 4, v210
	v_add_u32_e32 v214, s4, v210
	s_lshl_b32 s4, s54, 8
	s_add_u32 s4, s68, s4
	s_addc_u32 s5, s69, 0
	global_load_dword v96, v207, s[4:5]
	global_load_dword v97, v207, s[4:5] offset:32
	global_load_dword v98, v207, s[4:5] offset:64
	global_load_dword v99, v207, s[4:5] offset:96
	global_load_dword v100, v207, s[4:5] offset:128
	global_load_dword v101, v207, s[4:5] offset:160
	global_load_dword v102, v207, s[4:5] offset:192
	global_load_dword v103, v207, s[4:5] offset:224
	global_load_dwordx4 v[6:9], v209, s[76:77]
	s_add_u32 s76, s76, s79
	s_addc_u32 s77, s77, 0
	global_load_dwordx4 v[10:13], v209, s[76:77]
	s_add_u32 s76, s76, s79
	s_addc_u32 s77, s77, 0
	global_load_dwordx4 v[14:17], v209, s[76:77]
	s_add_u32 s76, s76, s79
	s_addc_u32 s77, s77, 0
	global_load_dwordx4 v[18:21], v209, s[76:77]
	s_add_u32 s76, s76, s79
	s_addc_u32 s77, s77, 0
	global_load_dwordx4 v[22:25], v209, s[76:77]
	s_add_u32 s76, s76, s79
	s_addc_u32 s77, s77, 0
	global_load_dwordx4 v[26:29], v209, s[76:77]
	s_add_u32 s76, s76, s79
	s_addc_u32 s77, s77, 0
	global_load_dwordx4 v[30:33], v209, s[76:77]
	s_add_u32 s76, s76, s79
	s_addc_u32 s77, s77, 0
	global_load_dwordx4 v[34:37], v209, s[76:77]
	s_add_u32 s52, s52, 1

.Ltail_gk_B:
	v_mul_f32_e32 v217, v104, v215
	v_mul_f32_e32 v38, v38, v217
	v_mul_f32_e32 v39, v39, v217
	v_mul_f32_e32 v40, v40, v217
	v_mul_f32_e32 v41, v41, v217
	ds_write_b32 v205, v38 offset:0
	ds_write_b32 v205, v39 offset:4
	ds_write_b32 v205, v40 offset:8
	ds_write_b32 v205, v41 offset:12
	v_mul_f32_e32 v217, v105, v215
	v_mul_f32_e32 v42, v42, v217
	v_mul_f32_e32 v43, v43, v217
	v_mul_f32_e32 v44, v44, v217
	v_mul_f32_e32 v45, v45, v217
	ds_write_b32 v205, v42 offset:1056
	ds_write_b32 v205, v43 offset:1060
	ds_write_b32 v205, v44 offset:1064
	ds_write_b32 v205, v45 offset:1068
	v_mul_f32_e32 v217, v106, v215
	v_mul_f32_e32 v46, v46, v217
	v_mul_f32_e32 v47, v47, v217
	v_mul_f32_e32 v48, v48, v217
	v_mul_f32_e32 v49, v49, v217
	ds_write_b32 v205, v46 offset:2112
	ds_write_b32 v205, v47 offset:2116
	ds_write_b32 v205, v48 offset:2120
	ds_write_b32 v205, v49 offset:2124
	v_mul_f32_e32 v217, v107, v215
	v_mul_f32_e32 v58, v58, v217
	v_mul_f32_e32 v59, v59, v217
	v_mul_f32_e32 v60, v60, v217
	v_mul_f32_e32 v61, v61, v217
	ds_write_b32 v205, v58 offset:3168
	ds_write_b32 v205, v59 offset:3172
	ds_write_b32 v205, v60 offset:3176
	ds_write_b32 v205, v61 offset:3180
	v_mul_f32_e32 v217, v108, v215
	v_mul_f32_e32 v62, v62, v217
	v_mul_f32_e32 v63, v63, v217
	v_mul_f32_e32 v64, v64, v217
	v_mul_f32_e32 v65, v65, v217
	ds_write_b32 v205, v62 offset:4224
	ds_write_b32 v205, v63 offset:4228
	ds_write_b32 v205, v64 offset:4232
	ds_write_b32 v205, v65 offset:4236
	v_mul_f32_e32 v217, v109, v215
	v_mul_f32_e32 v66, v66, v217
	v_mul_f32_e32 v67, v67, v217
	v_mul_f32_e32 v68, v68, v217
	v_mul_f32_e32 v69, v69, v217
	ds_write_b32 v205, v66 offset:5280
	ds_write_b32 v205, v67 offset:5284
	ds_write_b32 v205, v68 offset:5288
	ds_write_b32 v205, v69 offset:5292
	v_mul_f32_e32 v217, v110, v215
	v_mul_f32_e32 v88, v88, v217
	v_mul_f32_e32 v89, v89, v217
	v_mul_f32_e32 v90, v90, v217
	v_mul_f32_e32 v91, v91, v217
	ds_write_b32 v205, v88 offset:6336
	ds_write_b32 v205, v89 offset:6340
	ds_write_b32 v205, v90 offset:6344
	ds_write_b32 v205, v91 offset:6348
	v_mul_f32_e32 v217, v111, v215
	v_mul_f32_e32 v92, v92, v217
	v_mul_f32_e32 v93, v93, v217
	v_mul_f32_e32 v94, v94, v217
	v_mul_f32_e32 v95, v95, v217
	ds_write_b32 v205, v92 offset:7392
	ds_write_b32 v205, v93 offset:7396
	ds_write_b32 v205, v94 offset:7400
	ds_write_b32 v205, v95 offset:7404
	s_waitcnt lgkmcnt(0)
	ds_read2_b32 v[144:145], v206 offset0:0 offset1:33
	ds_read2_b32 v[146:147], v206 offset0:66 offset1:99
	ds_read2_b32 v[148:149], v206 offset0:132 offset1:165
	ds_read2_b32 v[150:151], v206 offset0:198 offset1:231
	s_waitcnt lgkmcnt(3)
	v_cvt_pk_bf16_f32 v152, v144, v145
	s_waitcnt lgkmcnt(2)
	v_cvt_pk_bf16_f32 v153, v146, v147
	s_waitcnt lgkmcnt(1)
	v_cvt_pk_bf16_f32 v154, v148, v149
	s_waitcnt lgkmcnt(0)
	v_cvt_pk_bf16_f32 v155, v150, v151
	s_mov_b64 s[6:7], s[50:51]
	global_store_dwordx4 v216, v[152:155], s[6:7]
	ds_read2_b32 v[144:145], v206 offset0:8 offset1:41
	ds_read2_b32 v[146:147], v206 offset0:74 offset1:107
	ds_read2_b32 v[148:149], v206 offset0:140 offset1:173
	ds_read2_b32 v[150:151], v206 offset0:206 offset1:239
	s_waitcnt lgkmcnt(3)
	v_cvt_pk_bf16_f32 v156, v144, v145
	s_waitcnt lgkmcnt(2)
	v_cvt_pk_bf16_f32 v157, v146, v147
	s_waitcnt lgkmcnt(1)
	v_cvt_pk_bf16_f32 v158, v148, v149
	s_waitcnt lgkmcnt(0)
	v_cvt_pk_bf16_f32 v159, v150, v151
	s_add_u32 s6, s6, 0x8000
	s_addc_u32 s7, s7, 0
	global_store_dwordx4 v216, v[156:159], s[6:7]
	ds_read2_b32 v[144:145], v206 offset0:16 offset1:49
	ds_read2_b32 v[146:147], v206 offset0:82 offset1:115
	ds_read2_b32 v[148:149], v206 offset0:148 offset1:181
	ds_read2_b32 v[150:151], v206 offset0:214 offset1:247
	s_waitcnt lgkmcnt(3)
	v_cvt_pk_bf16_f32 v152, v144, v145
	s_waitcnt lgkmcnt(2)
	v_cvt_pk_bf16_f32 v153, v146, v147
	s_waitcnt lgkmcnt(1)
	v_cvt_pk_bf16_f32 v154, v148, v149
	s_waitcnt lgkmcnt(0)
	v_cvt_pk_bf16_f32 v155, v150, v151
	s_add_u32 s6, s6, 0x8000
	s_addc_u32 s7, s7, 0
	global_store_dwordx4 v216, v[152:155], s[6:7]
	ds_read2_b32 v[144:145], v206 offset0:24 offset1:57
	ds_read2_b32 v[146:147], v206 offset0:90 offset1:123
	ds_read2_b32 v[148:149], v206 offset0:156 offset1:189
	ds_read2_b32 v[150:151], v206 offset0:222 offset1:255
	s_waitcnt lgkmcnt(3)
	v_cvt_pk_bf16_f32 v156, v144, v145
	s_waitcnt lgkmcnt(2)
	v_cvt_pk_bf16_f32 v157, v146, v147
	s_waitcnt lgkmcnt(1)
	v_cvt_pk_bf16_f32 v158, v148, v149
	s_waitcnt lgkmcnt(0)
	v_cvt_pk_bf16_f32 v159, v150, v151
	s_add_u32 s6, s6, 0x8000
	s_addc_u32 s7, s7, 0
	global_store_dwordx4 v216, v[156:159], s[6:7]
	s_cmp_eq_u32 s52, 0
	s_cbranch_scc1 .Ltail_end
	s_sub_u32 s52, s52, 1
	s_add_u32 s70, s70, s71
	s_cmp_lt_u32 s70, 0x2520
	s_cbranch_scc0 .Ltail_ni_r2
	s_cmp_lt_u32 s70, 0x1d20
	s_cbranch_scc0 .Ltail_m0_r2
	s_mul_hi_u32 s54, s70, 0x1194539
	s_mul_i32 s4, s54, 0xe9
	s_sub_u32 s55, s70, s4
	s_mov_b32 s47, 1
	s_movk_i32 s78, 0x7460
	s_mov_b64 s[56:57], s[64:65]
	s_mov_b64 s[50:51], s[66:67]
	s_branch .Ltail_cm_r2

.Ltail_wd_r2:
	s_cmp_eq_u32 s58, 0
	s_cbranch_scc0 .Ltail_gk_C
	v_mov_b32_e32 v240, 1.0
	v_mov_b32_e32 v241, 1.0
	v_mov_b32_e32 v242, 1.0
	v_mov_b32_e32 v243, 1.0
	v_mov_b32_e32 v244, 1.0
	v_mov_b32_e32 v245, 1.0
	v_mov_b32_e32 v246, 1.0
	v_mov_b32_e32 v247, 1.0
.Ltail_gk_C:
	v_mul_f32_e32 v217, v240, v248
	v_mul_f32_e32 v178, v178, v217
	v_mul_f32_e32 v179, v179, v217
	v_mul_f32_e32 v180, v180, v217
	v_mul_f32_e32 v181, v181, v217
	ds_write_b32 v205, v178 offset:0
	ds_write_b32 v205, v179 offset:4
	ds_write_b32 v205, v180 offset:8
	ds_write_b32 v205, v181 offset:12
	v_mul_f32_e32 v217, v241, v248
	v_mul_f32_e32 v182, v182, v217
	v_mul_f32_e32 v183, v183, v217
	v_mul_f32_e32 v184, v184, v217
	v_mul_f32_e32 v185, v185, v217
	ds_write_b32 v205, v182 offset:1056
	ds_write_b32 v205, v183 offset:1060
	ds_write_b32 v205, v184 offset:1064
	ds_write_b32 v205, v185 offset:1068
	v_mul_f32_e32 v217, v242, v248
	v_mul_f32_e32 v186, v186, v217
	v_mul_f32_e32 v187, v187, v217
	v_mul_f32_e32 v188, v188, v217
	v_mul_f32_e32 v189, v189, v217
	ds_write_b32 v205, v186 offset:2112
	ds_write_b32 v205, v187 offset:2116
	ds_write_b32 v205, v188 offset:2120
	ds_write_b32 v205, v189 offset:2124
	v_mul_f32_e32 v217, v243, v248
	v_mul_f32_e32 v220, v220, v217
	v_mul_f32_e32 v221, v221, v217
	v_mul_f32_e32 v222, v222, v217
	v_mul_f32_e32 v223, v223, v217
	ds_write_b32 v205, v220 offset:3168
	ds_write_b32 v205, v221 offset:3172
	ds_write_b32 v205, v222 offset:3176
	ds_write_b32 v205, v223 offset:3180
	v_mul_f32_e32 v217, v244, v248
	v_mul_f32_e32 v224, v224, v217
	v_mul_f32_e32 v225, v225, v217
	v_mul_f32_e32 v226, v226, v217
	v_mul_f32_e32 v227, v227, v217
	ds_write_b32 v205, v224 offset:4224
	ds_write_b32 v205, v225 offset:4228
	ds_write_b32 v205, v226 offset:4232
	ds_write_b32 v205, v227 offset:4236
	v_mul_f32_e32 v217, v245, v248
	v_mul_f32_e32 v228, v228, v217
	v_mul_f32_e32 v229, v229, v217
	v_mul_f32_e32 v230, v230, v217
	v_mul_f32_e32 v231, v231, v217
	ds_write_b32 v205, v228 offset:5280
	ds_write_b32 v205, v229 offset:5284
	ds_write_b32 v205, v230 offset:5288
	ds_write_b32 v205, v231 offset:5292
	v_mul_f32_e32 v217, v246, v248
	v_mul_f32_e32 v232, v232, v217
	v_mul_f32_e32 v233, v233, v217
	v_mul_f32_e32 v234, v234, v217
	v_mul_f32_e32 v235, v235, v217
	ds_write_b32 v205, v232 offset:6336
	ds_write_b32 v205, v233 offset:6340
	ds_write_b32 v205, v234 offset:6344
	ds_write_b32 v205, v235 offset:6348
	v_mul_f32_e32 v217, v247, v248
	v_mul_f32_e32 v236, v236, v217
	v_mul_f32_e32 v237, v237, v217
	v_mul_f32_e32 v238, v238, v217
	v_mul_f32_e32 v239, v239, v217
	ds_write_b32 v205, v236 offset:7392
	ds_write_b32 v205, v237 offset:7396
	ds_write_b32 v205, v238 offset:7400
	ds_write_b32 v205, v239 offset:7404
	s_waitcnt lgkmcnt(0)
	ds_read2_b32 v[144:145], v206 offset0:0 offset1:33
	ds_read2_b32 v[146:147], v206 offset0:66 offset1:99
	ds_read2_b32 v[148:149], v206 offset0:132 offset1:165
	ds_read2_b32 v[150:151], v206 offset0:198 offset1:231
	s_waitcnt lgkmcnt(3)
	v_cvt_pk_bf16_f32 v152, v144, v145
	s_waitcnt lgkmcnt(2)
	v_cvt_pk_bf16_f32 v153, v146, v147
	s_waitcnt lgkmcnt(1)
	v_cvt_pk_bf16_f32 v154, v148, v149
	s_waitcnt lgkmcnt(0)
	v_cvt_pk_bf16_f32 v155, v150, v151
	s_mov_b64 s[6:7], s[60:61]
	global_store_dwordx4 v249, v[152:155], s[6:7]
	ds_read2_b32 v[144:145], v206 offset0:8 offset1:41
	ds_read2_b32 v[146:147], v206 offset0:74 offset1:107
	ds_read2_b32 v[148:149], v206 offset0:140 offset1:173
	ds_read2_b32 v[150:151], v206 offset0:206 offset1:239
	s_waitcnt lgkmcnt(3)
	v_cvt_pk_bf16_f32 v156, v144, v145
	s_waitcnt lgkmcnt(2)
	v_cvt_pk_bf16_f32 v157, v146, v147
	s_waitcnt lgkmcnt(1)
	v_cvt_pk_bf16_f32 v158, v148, v149
	s_waitcnt lgkmcnt(0)
	v_cvt_pk_bf16_f32 v159, v150, v151
	s_add_u32 s6, s6, 0x8000
	s_addc_u32 s7, s7, 0
	global_store_dwordx4 v249, v[156:159], s[6:7]
	ds_read2_b32 v[144:145], v206 offset0:16 offset1:49
	ds_read2_b32 v[146:147], v206 offset0:82 offset1:115
	ds_read2_b32 v[148:149], v206 offset0:148 offset1:181
	ds_read2_b32 v[150:151], v206 offset0:214 offset1:247
	s_waitcnt lgkmcnt(3)
	v_cvt_pk_bf16_f32 v152, v144, v145
	s_waitcnt lgkmcnt(2)
	v_cvt_pk_bf16_f32 v153, v146, v147
	s_waitcnt lgkmcnt(1)
	v_cvt_pk_bf16_f32 v154, v148, v149
	s_waitcnt lgkmcnt(0)
	v_cvt_pk_bf16_f32 v155, v150, v151
	s_add_u32 s6, s6, 0x8000
	s_addc_u32 s7, s7, 0
	global_store_dwordx4 v249, v[152:155], s[6:7]
	ds_read2_b32 v[144:145], v206 offset0:24 offset1:57
	ds_read2_b32 v[146:147], v206 offset0:90 offset1:123
	ds_read2_b32 v[148:149], v206 offset0:156 offset1:189
	ds_read2_b32 v[150:151], v206 offset0:222 offset1:255
	s_waitcnt lgkmcnt(3)
	v_cvt_pk_bf16_f32 v156, v144, v145
	s_waitcnt lgkmcnt(2)
	v_cvt_pk_bf16_f32 v157, v146, v147
	s_waitcnt lgkmcnt(1)
	v_cvt_pk_bf16_f32 v158, v148, v149
	s_waitcnt lgkmcnt(0)
	v_cvt_pk_bf16_f32 v159, v150, v151
	s_add_u32 s6, s6, 0x8000
	s_addc_u32 s7, s7, 0
	global_store_dwordx4 v249, v[156:159], s[6:7]
	s_cmp_eq_u32 s52, 0
	s_cbranch_scc1 .Ltail_end
	s_sub_u32 s52, s52, 1
	s_branch .Ltail_loop

.LBB0_322:
	s_or_b64 exec, exec, s[4:5]
	v_lshrrev_b32_e32 v8, 5, v2
	v_lshlrev_b32_e32 v182, 2, v8
	v_and_b32_e32 v183, 31, v178
	v_or_b32_e32 v214, 3, v182
	v_cmp_lt_u32_e64 s[6:7], v214, v183
	v_or_b32_e32 v215, 8, v182
	v_or_b32_e32 v216, 9, v182
	v_writelane_b32 v254, s6, 50
	v_or_b32_e32 v217, 10, v182
	v_or_b32_e32 v218, 11, v182
	v_writelane_b32 v254, s7, 51
	v_cmp_lt_u32_e64 s[6:7], v215, v183
	v_or_b32_e32 v219, 16, v182
	v_or_b32_e32 v220, 17, v182
	v_writelane_b32 v254, s6, 52
	v_or_b32_e32 v221, 18, v182
	v_or_b32_e32 v222, 19, v182
	v_writelane_b32 v254, s7, 53
	v_cmp_lt_u32_e64 s[6:7], v216, v183
	s_mov_b32 s63, s15
	v_or_b32_e32 v223, 24, v182
	v_writelane_b32 v254, s6, 54
	s_lshl_b64 s[4:5], s[62:63], 2
	v_lshrrev_b32_e32 v10, 3, v178
	v_writelane_b32 v254, s7, 55
	v_cmp_lt_u32_e64 s[6:7], v217, v183
	s_add_u32 s24, s30, s4
	v_lshlrev_b32_e32 v176, 3, v8
	v_writelane_b32 v254, s6, 56
	v_lshlrev_b32_e32 v210, 4, v8
	v_and_b32_e32 v10, 4, v10
	v_writelane_b32 v254, s7, 57
	v_cmp_lt_u32_e64 s[6:7], v218, v183
	v_bfe_u32 v11, v178, 2, 2
	v_or_b32_e32 v224, 25, v182
	v_writelane_b32 v254, s6, 58
	v_lshrrev_b32_e32 v8, 1, v178
	s_addc_u32 s25, s31, s5
	v_writelane_b32 v254, s7, 59
	v_cmp_lt_u32_e64 s[6:7], v219, v183
	s_lshl_b32 s46, s14, 5
	v_and_b32_e32 v14, 16, v178
	v_writelane_b32 v254, s6, 60
	v_lshlrev_b32_e32 v2, 2, v2
	v_and_b32_e32 v227, 16, v8
	v_writelane_b32 v254, s7, 61
	v_cmp_lt_u32_e64 s[6:7], v220, v183
	v_or_b32_e32 v8, v11, v10
	v_and_or_b32 v2, v2, 12, v14
	v_writelane_b32 v254, s6, 62
	v_or_b32_e32 v225, 26, v182
	s_add_i32 s4, s46, 32
	v_writelane_b32 v254, s7, 63
	v_cmp_lt_u32_e64 s[6:7], v221, v183
	v_or_b32_e32 v14, 16, v8
	v_lshlrev_b32_e32 v211, 1, v2
	v_writelane_b32 v255, s6, 0
	v_or_b32_e32 v2, s4, v183
	v_or_b32_e32 v15, s4, v8
	v_writelane_b32 v255, s7, 1
	v_cmp_lt_u32_e64 s[6:7], v222, v183
	v_or_b32_e32 v16, s4, v14
	s_add_i32 s4, s46, 64
	v_writelane_b32 v255, s6, 2
	v_or_b32_e32 v226, 27, v182
	v_or_b32_e32 v17, s4, v8
	v_writelane_b32 v255, s7, 3
	v_cmp_lt_u32_e64 s[6:7], v223, v183
	v_or_b32_e32 v18, s4, v14
	s_add_i32 s4, s46, 0x60
	v_writelane_b32 v255, s6, 4
	v_or_b32_e32 v209, s46, v183
	v_or_b32_e32 v19, s4, v8
	v_writelane_b32 v255, s7, 5
	v_cmp_lt_u32_e64 s[6:7], v224, v183
	v_or_b32_e32 v14, s4, v14
	s_add_i32 s4, s46, 0x80
	v_writelane_b32 v255, s6, 6
	v_ashrrev_i32_e32 v205, 3, v178
	s_movk_i32 s5, 0x90
	v_writelane_b32 v255, s7, 7
	v_cmp_lt_u32_e64 s[6:7], v225, v183
	v_subrev_u32_e32 v20, s46, v209
	v_or_b32_e32 v21, s4, v183
	v_writelane_b32 v255, s6, 8
	v_or3_b32 v22, v10, s4, v11
	s_add_i32 s4, s46, 0x90
	v_writelane_b32 v255, s7, 9
	v_cmp_lt_u32_e64 s[6:7], v226, v183
	v_mul_lo_u32 v207, v205, s5
	v_mul_lo_u32 v9, v209, s5
	v_writelane_b32 v255, s6, 10
	v_or3_b32 v12, v10, s46, v11
	v_mul_lo_u32 v2, v2, s5
	v_writelane_b32 v255, s7, 11
	v_mul_lo_u32 v21, v21, s5
	v_or3_b32 v10, s4, v10, v11
	v_cmp_gt_i32_e64 s[4:5], v182, v20
	v_or_b32_e32 v213, 2, v182
	v_xor_b32_e32 v4, 32, v198
	v_writelane_b32 v255, s4, 12
	v_add_u32_e32 v0, 64, v0
	v_cmp_lt_i32_e32 vcc, v4, v0
	v_writelane_b32 v255, s5, 13
	v_cmp_gt_i32_e64 s[4:5], v213, v20
	v_cndmask_b32_e32 v0, v198, v4, vcc
	v_lshlrev_b32_e32 v179, 2, v0
	v_writelane_b32 v255, s4, 14
	v_lshlrev_b32_e32 v0, 4, v178
	v_mul_u32_u24_e32 v230, 0xc0, v8
	v_writelane_b32 v255, s5, 15
	v_cmp_gt_i32_e64 s[4:5], v214, v20
	v_and_b32_e32 v8, 3, v178
	v_and_b32_e32 v0, 0x70, v0
	v_writelane_b32 v255, s4, 16
	v_mul_lo_u32 v208, v205, s23
	v_mul_lo_u32 v12, v12, s23
	v_writelane_b32 v255, s5, 17
	v_cmp_gt_i32_e64 s[4:5], v215, v20
	v_mul_lo_u32 v15, v15, s23
	v_mul_lo_u32 v16, v16, s23
	v_writelane_b32 v255, s4, 18
	v_mul_lo_u32 v17, v17, s23
	v_mul_lo_u32 v18, v18, s23
	v_writelane_b32 v255, s5, 19
	v_cmp_gt_i32_e64 s[4:5], v216, v20
	v_mul_lo_u32 v19, v19, s23
	v_mul_lo_u32 v14, v14, s23
	v_writelane_b32 v255, s4, 20
	v_mul_lo_u32 v22, v22, s23
	v_mul_lo_u32 v10, v10, s23
	v_writelane_b32 v255, s5, 21
	v_cmp_gt_i32_e64 s[4:5], v217, v20
	v_and_b32_e32 v3, 32, v3
	v_lshlrev_b32_e32 v8, 3, v8
	v_lshl_add_u64 v[180:181], s[0:1], 0, v[0:1]
	v_add_u32_e32 v206, 0, v0
	v_add_u32_e32 v0, 0x3000, v208
	v_add_u32_e32 v4, 0x6000, v208
	v_add_u32_e32 v5, 0x9000, v208
	v_add_u32_e32 v6, 0xc000, v208
	v_add_u32_e32 v7, 0xf000, v208
	v_add_u32_e32 v9, 0, v9
	v_add_u32_e32 v13, 0, v12
	v_or_b32_e32 v212, 1, v182
	v_add_u32_e32 v2, 0, v2
	v_add_u32_e32 v15, 0, v15
	v_add_u32_e32 v16, 0, v16
	v_add_u32_e32 v17, 0, v17
	v_add_u32_e32 v18, 0, v18
	v_add_u32_e32 v19, 0, v19
	v_add_u32_e32 v14, 0, v14
	v_add_u32_e32 v21, 0, v21
	v_add_u32_e32 v22, 0, v22
	v_add_u32_e32 v10, 0, v10
	v_writelane_b32 v255, s4, 22
	s_movk_i32 s6, 0x80
	v_mul_u32_u24_e32 v229, 0x90, v183
	v_or3_b32 v231, v12, v3, v8
	s_mulk_i32 s14, 0x1200
	v_max_i32_e32 v3, 0x80, v209
	s_mov_b32 s70, s62
	v_cmp_lt_u32_e64 s[72:73], v182, v183
	v_cmp_lt_u32_e64 s[74:75], v212, v183
	v_cmp_lt_u32_e64 s[78:79], v213, v183
	v_cmp_lt_i32_e64 s[44:45], v182, v20
	v_writelane_b32 v255, s5, 23
	v_cmp_gt_i32_e64 s[56:57], v218, v20
	v_cmp_gt_i32_e64 s[58:59], v219, v20
	v_cmp_gt_i32_e64 s[60:61], v220, v20
	v_cmp_gt_i32_e64 s[62:63], v221, v20
	v_cmp_gt_i32_e64 s[64:65], v222, v20
	v_cmp_gt_i32_e64 s[66:67], v223, v20
	v_cmp_gt_i32_e64 s[40:41], v224, v20
	v_cmp_gt_i32_e64 s[8:9], v225, v20
	v_cmp_gt_i32_e64 s[4:5], v226, v20
	v_cmp_gt_i32_e64 s[6:7], s6, v178
	v_lshlrev_b32_e32 v228, 3, v178
	v_add3_u32 v232, s14, v229, v210
	v_subrev_u32_e32 v233, s46, v3
	s_or_b32 s71, s46, 31
	v_add_u32_e32 v196, v206, v0
	v_add_u32_e32 v202, v206, v4
	v_add_u32_e32 v203, v206, v5
	v_add_u32_e32 v204, v206, v6
	v_add_u32_e32 v238, v206, v7
	v_add_u32_e32 v239, v9, v210
	v_add_u32_e32 v240, v13, v211
	v_add_u32_e32 v241, v2, v227
	v_add_u32_e32 v242, v15, v211
	v_add_u32_e32 v243, v16, v211
	v_add_u32_e32 v244, v17, v211
	v_add_u32_e32 v245, v18, v211
	v_add_u32_e32 v246, v19, v211
	v_add_u32_e32 v247, v14, v211
	v_add_u32_e32 v248, v21, v210
	v_add_u32_e32 v249, v22, v211
	v_add_u32_e32 v250, v10, v211
	s_waitcnt lgkmcnt(0)
	s_barrier
	s_mov_b32 s32, 0
	s_branch .LBB0_325

.LBB0_325:
	s_and_saveexec_b64 s[10:11], s[38:39]
	s_cbranch_execz .LBB0_329
	s_cmp_eq_u32 s32, 1
	s_cbranch_scc0 .Lq_fresh
	s_waitcnt vmcnt(0)
	v_mov_b32_e32 v2, v164
	v_mov_b32_e32 v0, 0
	s_branch .Lq_join
.Lq_fresh:
	s_mov_b64 s[42:43], exec
	v_mbcnt_lo_u32_b32 v0, s42, 0
	v_mbcnt_hi_u32_b32 v0, s43, v0
	v_cmp_eq_u32_e32 vcc, 0, v0
	s_and_saveexec_b64 s[26:27], vcc
	s_cbranch_execz .LBB0_328
	s_bcnt1_i32_b64 s14, s[42:43]
	v_mov_b32_e32 v2, s14
	global_atomic_add v2, v1, v2, s[24:25] sc0

.Lq_join:
	s_waitcnt vmcnt(0)
	v_readfirstlane_b32 s14, v2
	s_mov_b64 s[26:27], src_shared_base
	s_nop 0
	v_add_u32_e32 v0, s14, v0
	s_add_i32 s14, 0, 0x20040
	s_cmp_lg_u32 s14, -1
	s_cselect_b32 s14, s14, 0
	s_cselect_b32 s26, s27, 0
	v_mov_b32_e32 v2, s14
	v_mov_b32_e32 v3, s26
	flat_store_dword v[2:3], v0 sc0 sc1
	s_waitcnt vmcnt(0)
.LBB0_329:
	s_or_b64 exec, exec, s[10:11]
	s_mov_b32 s32, 0
	s_mov_b64 s[10:11], src_shared_base
	s_add_i32 s10, 0, 0x20040
	s_cmp_lg_u32 s10, -1
	s_cselect_b32 s10, s10, 0
	s_cselect_b32 s11, s11, 0
	v_mov_b32_e32 v2, s10
	v_mov_b32_e32 v3, s11
	s_waitcnt lgkmcnt(0)
	s_barrier
	flat_load_dword v0, v[2:3] sc0 sc1
	s_waitcnt vmcnt(0)
	s_mov_b64 s[10:11], -1
	s_waitcnt lgkmcnt(0)
	s_barrier
	v_readfirstlane_b32 s42, v0
	s_cmpk_gt_i32 s42, 0x747
	s_cbranch_scc1 .LBB0_324
	s_cmpk_gt_i32 s42, 0x47
	s_cbranch_scc0 .LBB0_405
	s_cmpk_gt_u32 s42, 0x2c7
	s_cbranch_scc0 .LBB0_346
	s_mov_b64 s[10:11], exec
	s_and_b64 exec, exec, s[38:39]
	s_cbranch_execz .Lq_noissue
	v_mov_b32_e32 v165, 1
	global_atomic_add v164, v1, v165, s[24:25] sc0
.Lq_noissue:
	s_mov_b64 exec, s[10:11]
	s_mov_b32 s32, 1
	s_add_i32 s14, s42, 0xfbb8
	s_add_i32 s10, s42, 0xfffffd38
	s_add_i32 s11, s42, 0xfffffbb8
	s_and_b32 s14, s14, 0xffff
	s_cmpk_lt_u32 s14, 0x180
	s_cselect_b32 s14, 2, 4
	s_cmpk_lt_u32 s10, 0x180
	s_cselect_b32 s47, 0, s14
	s_cmpk_lt_u32 s11, 0x180
	s_cselect_b32 s11, 3, 1
	s_cselect_b32 s14, 7, 1
	s_cmpk_lt_u32 s10, 0x180
	s_cselect_b32 s11, 5, s11
	s_cselect_b32 s14, 31, s14
	s_and_b32 s26, s10, 0xffff
	s_mul_i32 s26, s26, 0xaaab
	s_lshr_b32 s27, s26, 24
	s_mul_i32 s26, s27, 0x180
	s_sub_i32 s10, s10, s26
	s_and_b32 s43, s10, 0xffff
	s_and_b32 s43, s14, s43
	s_bfe_u32 s26, s10, 0xb0005
	s_and_b32 s10, s10, 31
	s_lshl_b32 s49, s43, 8
	s_lshr_b32 s48, s10, s11
	v_add_u32_e32 v0, s49, v205
	s_lshl_b32 s14, s26, 7
	s_movk_i32 s10, 0x7f
	v_lshl_add_u64 v[50:51], v[180:181], 0, s[14:15]
	v_cmp_lt_i32_e32 vcc, s10, v0
	v_mov_b32_e32 v2, 0
	v_mov_b32_e32 v6, 0
	v_mov_b32_e32 v7, 0
	v_mov_b32_e32 v8, 0
	v_mov_b32_e32 v9, 0
	v_mov_b32_e32 v10, 0
	v_mov_b32_e32 v11, 0
	v_mov_b32_e32 v12, 0
	v_mov_b32_e32 v13, 0
	s_and_saveexec_b64 s[10:11], vcc
	s_cbranch_execz .LBB0_334
	v_add_u32_e32 v3, 0xffffff80, v0
	v_lshlrev_b32_e32 v3, s47, v3
	v_add_u32_e32 v3, s48, v3
	v_mad_u64_u32 v[4:5], s[50:51], v3, s35, v[50:51]
	global_load_dwordx4 v[6:9], v[4:5], off offset:1536
	global_load_dwordx4 v[10:13], v[4:5], off offset:3072
